# attention K/V staging in write-after-barrier form: barrier, write tile it+1 to the other buffer, re-issue loads for tile it+2
# speedup vs baseline: 1.0035x; 1.0019x over previous
.LBB0_1729:
	s_and_b32 s0, s84, 1
	s_mul_i32 s1, s0, 0x4400
	s_add_i32 s16, s1, 0
	s_lshl_b32 s0, s0, 10
	s_add_i32 s15, s16, s0
	s_sub_i32 s32, 0x4400, s16
	s_sub_i32 s94, 0x400, s0
	s_add_i32 s94, s94, s32
	s_cmp_lg_u32 s84, 0
	s_cbranch_scc1 .Lattn_g15_u1
	v_add3_u32 v64, s16, v179, v177
	s_waitcnt vmcnt(3)
	ds_write_b128 v64, v[100:103]
	v_add3_u32 v64, s16, v180, v177
	s_waitcnt vmcnt(2)
	ds_write_b128 v64, v[96:99]
	v_add3_u32 v64, s15, v176, v178
	s_waitcnt vmcnt(1)
	ds_write_b128 v64, v[104:107] offset:34816
	s_waitcnt vmcnt(0)
	ds_write_b128 v64, v[108:111] offset:44032
	v_lshl_add_u64 v[66:67], v[152:153], 0, s[98:99]
	v_lshl_add_u64 v[64:65], v[152:153], 0, s[100:101]
	global_load_dwordx4 v[100:103], v[66:67], off
	global_load_dwordx4 v[96:99], v[64:65], off
	v_lshl_add_u64 v[66:67], v[150:151], 0, s[44:45]
	v_lshl_add_u64 v[64:65], v[150:151], 0, s[46:47]
	global_load_dwordx4 v[104:107], v[66:67], off offset:128
	global_load_dwordx4 v[108:111], v[64:65], off offset:128
	s_add_u32 s98, s98, 0x4000
	s_addc_u32 s99, s99, 0
	s_add_u32 s100, s100, 0x4000
	s_addc_u32 s101, s101, 0
	s_add_u32 s44, s44, 0x80
	s_addc_u32 s45, s45, 0
	s_add_u32 s46, s46, 0x80
	s_addc_u32 s47, s47, 0
.Lattn_g15_u1:
	s_waitcnt lgkmcnt(0)
	s_barrier
	v_add3_u32 v208, s32, v179, v177
	s_waitcnt vmcnt(3)
	ds_write_b128 v208, v[100:103]
	v_add3_u32 v208, s32, v180, v177
	s_waitcnt vmcnt(2)
	ds_write_b128 v208, v[96:99]
	v_add3_u32 v208, s94, v176, v178
	s_waitcnt vmcnt(1)
	ds_write_b128 v208, v[104:107] offset:34816
	s_waitcnt vmcnt(0)
	ds_write_b128 v208, v[108:111] offset:44032
	v_lshl_add_u64 v[66:67], v[152:153], 0, s[98:99]
	v_lshl_add_u64 v[64:65], v[152:153], 0, s[100:101]
	global_load_dwordx4 v[100:103], v[66:67], off
	global_load_dwordx4 v[96:99], v[64:65], off
	v_lshl_add_u64 v[66:67], v[150:151], 0, s[44:45]
	s_lshr_b32 s0, s84, 2
	v_lshl_add_u64 v[64:65], v[150:151], 0, s[46:47]
	s_cmp_eq_u32 s0, s81
	global_load_dwordx4 v[104:107], v[66:67], off offset:128
	global_load_dwordx4 v[108:111], v[64:65], off offset:128
	s_cselect_b64 s[8:9], -1, 0
	s_lshl_b32 s1, 1, s0
	v_and_b32_e32 v64, s1, v173
	s_cmp_lg_u32 s0, s81
	v_cmp_ne_u32_e64 s[0:1], 0, v64
	s_mov_b64 s[4:5], -1
	s_cbranch_scc0 .LBB0_1732
	v_cndmask_b32_e64 v64, 0, 1, s[0:1]
	v_cmp_ne_u32_e32 vcc, 0, v64
	s_cmp_lg_u64 vcc, 0
	s_cselect_b64 s[10:11], -1, 0
	s_and_b32 s17, s84, 3
	s_cbranch_execz .LBB0_1733

.LBB0_1740:
	s_and_b32 s0, s14, 1
	s_mul_i32 s1, s0, 0x4400
	s_add_i32 s16, s1, 0
	s_waitcnt vmcnt(0)
	s_lshl_b32 s0, s0, 10
	s_add_i32 s15, s16, s0
	s_lshr_b32 s0, s14, 2
	s_cmp_eq_u32 s0, s81
	v_lshrrev_b32_e32 v64, s0, v173
	s_cselect_b64 s[8:9], -1, 0
	v_and_b32_e32 v64, 1, v64
	v_cmp_eq_u32_e64 s[0:1], 1, v64
	s_mov_b64 s[4:5], -1
	s_and_b64 vcc, exec, s[8:9]
	s_waitcnt lgkmcnt(0)
	s_barrier
	s_cbranch_vccnz .LBB0_1743
	v_cndmask_b32_e64 v64, 0, 1, s[0:1]
	v_cmp_ne_u32_e32 vcc, 0, v64
	s_cmp_lg_u64 vcc, 0
	s_cselect_b64 s[10:11], -1, 0
	s_and_b32 s14, s14, 3
	s_cbranch_execz .LBB0_1744

.LBB0_1772:
	s_and_b32 s0, s15, 1
	s_mul_i32 s1, s0, 0x4400
	s_add_i32 s17, s1, 0
	s_lshl_b32 s0, s0, 10
	s_add_i32 s16, s17, s0
	s_sub_i32 s32, 0x4400, s17
	s_sub_i32 s94, 0x400, s0
	s_add_i32 s94, s94, s32
	s_cmp_lg_u32 s15, 0
	s_cbranch_scc1 .Lattn_g15_u2
	v_add3_u32 v64, s17, v179, v177
	s_waitcnt vmcnt(3)
	ds_write_b128 v64, v[100:103]
	v_add3_u32 v64, s17, v180, v177
	s_waitcnt vmcnt(2)
	ds_write_b128 v64, v[96:99]
	v_add3_u32 v64, s16, v176, v178
	s_waitcnt vmcnt(1)
	ds_write_b128 v64, v[104:107] offset:34816
	s_waitcnt vmcnt(0)
	ds_write_b128 v64, v[108:111] offset:44032
	v_lshl_add_u64 v[66:67], v[152:153], 0, s[98:99]
	v_lshl_add_u64 v[64:65], v[152:153], 0, s[100:101]
	global_load_dwordx4 v[100:103], v[66:67], off
	global_load_dwordx4 v[96:99], v[64:65], off
	v_lshl_add_u64 v[66:67], v[150:151], 0, s[44:45]
	v_lshl_add_u64 v[64:65], v[150:151], 0, s[46:47]
	global_load_dwordx4 v[104:107], v[66:67], off offset:128
	global_load_dwordx4 v[108:111], v[64:65], off offset:128
	s_add_u32 s98, s98, 0x4000
	s_addc_u32 s99, s99, 0
	s_add_u32 s100, s100, 0x4000
	s_addc_u32 s101, s101, 0
	s_add_u32 s44, s44, 0x80
	s_addc_u32 s45, s45, 0
	s_add_u32 s46, s46, 0x80
	s_addc_u32 s47, s47, 0
.Lattn_g15_u2:
	s_waitcnt lgkmcnt(0)
	s_barrier
	v_add3_u32 v208, s32, v179, v177
	s_waitcnt vmcnt(3)
	ds_write_b128 v208, v[100:103]
	v_add3_u32 v208, s32, v180, v177
	s_waitcnt vmcnt(2)
	ds_write_b128 v208, v[96:99]
	v_add3_u32 v208, s94, v176, v178
	s_waitcnt vmcnt(1)
	ds_write_b128 v208, v[104:107] offset:34816
	s_waitcnt vmcnt(0)
	ds_write_b128 v208, v[108:111] offset:44032
	v_lshl_add_u64 v[66:67], v[152:153], 0, s[98:99]
	v_lshl_add_u64 v[64:65], v[152:153], 0, s[100:101]
	global_load_dwordx4 v[100:103], v[66:67], off
	global_load_dwordx4 v[96:99], v[64:65], off
	v_lshl_add_u64 v[66:67], v[150:151], 0, s[44:45]
	s_lshr_b32 s0, s15, 2
	v_lshl_add_u64 v[64:65], v[150:151], 0, s[46:47]
	s_cmp_eq_u32 s0, s80
	global_load_dwordx4 v[104:107], v[66:67], off offset:128
	global_load_dwordx4 v[108:111], v[64:65], off offset:128
	s_cselect_b64 s[8:9], -1, 0
	s_lshl_b32 s1, 1, s0
	v_and_b32_e32 v64, s1, v172
	s_cmp_lg_u32 s0, s80
	v_cmp_ne_u32_e64 s[0:1], 0, v64
	s_mov_b64 s[4:5], -1
	s_cbranch_scc0 .LBB0_1775
	v_cndmask_b32_e64 v64, 0, 1, s[0:1]
	v_cmp_ne_u32_e32 vcc, 0, v64
	s_cmp_lg_u64 vcc, 0
	s_cselect_b64 s[10:11], -1, 0
	s_and_b32 s18, s15, 3
	s_cbranch_execz .LBB0_1776

.LBB0_1783:
	s_and_b32 s0, s14, 1
	s_mul_i32 s1, s0, 0x4400
	s_add_i32 s15, s1, 0
	s_waitcnt vmcnt(0)
	s_lshl_b32 s0, s0, 10
	s_add_i32 s12, s15, s0
	s_lshr_b32 s0, s14, 2
	s_cmp_eq_u32 s0, s80
	v_lshrrev_b32_e32 v64, s0, v172
	s_cselect_b64 s[8:9], -1, 0
	v_and_b32_e32 v64, 1, v64
	v_cmp_eq_u32_e64 s[0:1], 1, v64
	s_mov_b64 s[4:5], -1
	s_and_b64 vcc, exec, s[8:9]
	s_waitcnt lgkmcnt(0)
	s_barrier
	s_cbranch_vccnz .LBB0_1786
	v_cndmask_b32_e64 v64, 0, 1, s[0:1]
	v_cmp_ne_u32_e32 vcc, 0, v64
	s_cmp_lg_u64 vcc, 0
	s_cselect_b64 s[10:11], -1, 0
	s_and_b32 s13, s14, 3
	s_cbranch_execz .LBB0_1787
